# ss-hoist + P9 block scan on all WGs + dead XB store removed in last FFN-down epilogue
# baseline (speedup 1.0000x reference)
; __device__ __forceinline__ unsigned pk(float lo, float hi) { return pg8::cvt_pk_bf16(lo, hi); }
; __device__ __forceinline__ float dot4(f32x4 v) { return (v[0] * v[0] + v[1] * v[1]) + (v[2] * v[2] + v[3] * v[3]); }
;     __device__ __forceinline__ void operator()(const pg8::f32x4 (&acc)[2][2][4][2], const pg8::Unit& u, int wr, int wc, int fr, int fq) const {
;         const int row0 = u.pm * 256 + wr * 64 + fr;
; #pragma unroll
;         for (int ai = 0; ai < 2; ++ai)
; #pragma unroll
;             for (int m = 0; m < 4; ++m) {
;                 const int row = row0 + ai * 128 + m * 16;
;                 const float* xi = (row < MP) ? xin_p + (size_t)row * DM : xin_s + (size_t)(row - MP) * DM;
;                 float sq = 0.f;
; #pragma unroll
;                 for (int bj = 0; bj < 2; ++bj) { const int col = u.pn * 256 + bj * 128 + wc * 32 + 8 * fq;
;                     const f32x4 a0 = *(const f32x4*)(xi + col) + acc[ai][bj][m][0], a1 = *(const f32x4*)(xi + col + 4) + acc[ai][bj][m][1];
;                     *(f32x4*)(xout + (size_t)row * DM + col) = a0; *(f32x4*)(xout + (size_t)row * DM + col + 4) = a1;
;                     u32x4 w; w.x = pk(a0[0], a0[1]); w.y = pk(a0[2], a0[3]); w.z = pk(a1[0], a1[1]); w.w = pk(a1[2], a1[3]);
;                     *(u32x4*)(xb + (size_t)row * DM + col) = w;
;                     sq += dot4(a0) + dot4(a1); }
;                 sq += __shfl_xor(sq, 16); sq += __shfl_xor(sq, 32);
;                 if (fq == 0) atomicAdd(ssout + row, sq);
;             }
.LBB0_2012:
	v_lshl_add_u32 v152, s58, 8, v163
	v_cmp_lt_i32_e32 vcc, s50, v152
	s_and_saveexec_b64 s[24:25], vcc
	s_xor_b64 s[24:25], exec, s[24:25]
	v_add_u32_e32 v138, 0xffffc000, v152
	v_lshlrev_b64 v[148:149], 12, v[138:139]
	v_lshl_add_u64 v[154:155], s[8:9], 0, v[148:149]
	v_mov_b32_e32 v153, v139
	s_andn2_saveexec_b64 s[24:25], s[24:25]
	v_ashrrev_i32_e32 v153, 31, v152
	v_lshlrev_b64 v[148:149], 12, v[152:153]
	v_lshl_add_u64 v[154:155], s[16:17], 0, v[148:149]
	s_or_b64 exec, exec, s[24:25]
	v_lshl_or_b32 v148, s57, 8, v165
	v_ashrrev_i32_e32 v149, 31, v148
	v_lshlrev_b64 v[150:151], 2, v[148:149]
	v_lshl_add_u64 v[154:155], v[154:155], 0, v[150:151]
	global_load_dwordx4 v[176:179], v[154:155], off
	global_load_dwordx4 v[180:183], v[154:155], off offset:16
	v_lshlrev_b64 v[184:185], 12, v[152:153]
	v_lshlrev_b64 v[186:187], 11, v[152:153]
	v_lshl_add_u64 v[184:185], s[16:17], 0, v[184:185]
	v_lshl_add_u64 v[186:187], s[64:65], 0, v[186:187]
	v_lshl_add_u64 v[188:189], v[148:149], 1, v[186:187]
	v_lshl_add_u64 v[190:191], v[184:185], 0, v[150:151]
	v_xor_b32_e32 v138, 32, v169
	s_waitcnt vmcnt(0)
	v_pk_add_f32 v[128:129], v[128:129], v[178:179]
	v_pk_add_f32 v[126:127], v[126:127], v[176:177]
	v_pk_add_f32 v[178:179], v[124:125], v[182:183]
	v_pk_add_f32 v[176:177], v[122:123], v[180:181]
	global_store_dwordx4 v[190:191], v[126:129], off
	global_store_dwordx4 v[190:191], v[176:179], off offset:16
	v_cvt_pk_bf16_f32 v122, v126, v127
	v_cvt_pk_bf16_f32 v123, v128, v129
	v_cvt_pk_bf16_f32 v124, v176, v177
	v_cvt_pk_bf16_f32 v125, v178, v179
	s_nop 0
	global_load_dwordx4 v[180:183], v[154:155], off offset:512
	global_load_dwordx4 v[184:187], v[154:155], off offset:528
	v_mul_f32_e32 v124, v127, v127
	v_mul_f32_e32 v125, v129, v129
	v_mul_f32_e32 v127, v177, v177
	v_mul_f32_e32 v129, v179, v179
	v_fmac_f32_e32 v124, v126, v126
	v_fmac_f32_e32 v125, v128, v128
	v_fmac_f32_e32 v127, v176, v176
	v_fmac_f32_e32 v129, v178, v178
	v_add_f32_e32 v124, v124, v125
	v_add_f32_e32 v125, v127, v129
	v_add_f32_e32 v128, v124, v125
	v_and_b32_e32 v123, 64, v169
	v_xor_b32_e32 v122, 16, v169
	v_add_u32_e32 v123, 64, v123
	v_cmp_lt_i32_e32 vcc, v122, v123
	s_waitcnt vmcnt(1)
	v_pk_add_f32 v[120:121], v[120:121], v[182:183]
	v_pk_add_f32 v[118:119], v[118:119], v[180:181]
	s_waitcnt vmcnt(0)
	v_pk_add_f32 v[126:127], v[116:117], v[186:187]
	v_pk_add_f32 v[124:125], v[114:115], v[184:185]
	v_mul_f32_e32 v114, v119, v119
	v_mul_f32_e32 v115, v121, v121
	v_mul_f32_e32 v116, v125, v125
	v_mul_f32_e32 v117, v127, v127
	v_fmac_f32_e32 v114, v118, v118
	v_fmac_f32_e32 v115, v120, v120
	v_fmac_f32_e32 v116, v124, v124
	v_fmac_f32_e32 v117, v126, v126
	v_add_f32_e32 v114, v114, v115
	v_add_f32_e32 v115, v116, v117
	v_cndmask_b32_e32 v122, v169, v122, vcc
	v_add_f32_e32 v114, v114, v115
	v_lshlrev_b32_e32 v122, 2, v122
	v_add_f32_e32 v114, v128, v114
	ds_bpermute_b32 v115, v122, v114
	v_cmp_lt_i32_e32 vcc, v138, v123
	global_store_dwordx4 v[190:191], v[118:121], off offset:512
	global_store_dwordx4 v[190:191], v[124:127], off offset:528
	v_cndmask_b32_e32 v116, v169, v138, vcc
	v_cvt_pk_bf16_f32 v176, v118, v119
	s_waitcnt lgkmcnt(0)
	v_add_f32_e32 v114, v114, v115
	v_lshlrev_b32_e32 v118, 2, v116
	ds_bpermute_b32 v115, v118, v114
	v_cvt_pk_bf16_f32 v177, v120, v121
	v_cvt_pk_bf16_f32 v178, v124, v125
	v_cvt_pk_bf16_f32 v179, v126, v127
	s_nop 0
	s_and_saveexec_b64 s[24:25], s[0:1]
	s_cbranch_execz .LBB0_2018
	s_waitcnt lgkmcnt(0)
	v_add_f32_e32 v116, v114, v115
	v_lshl_add_u64 v[114:115], v[152:153], 2, s[10:11]
	global_atomic_add_f32 v[114:115], v116, off
.LBB0_2018:
	s_or_b64 exec, exec, s[24:25]
	s_waitcnt lgkmcnt(0)
	v_or_b32_e32 v114, 16, v152
	v_cmp_lt_i32_e32 vcc, s50, v114
	s_and_saveexec_b64 s[24:25], vcc
	s_xor_b64 s[24:25], exec, s[24:25]
	v_add_u32_e32 v138, 0xffffc010, v152
	v_lshlrev_b64 v[116:117], 12, v[138:139]
	v_lshl_add_u64 v[116:117], s[8:9], 0, v[116:117]
	v_mov_b32_e32 v115, v139
	s_andn2_saveexec_b64 s[24:25], s[24:25]
	v_ashrrev_i32_e32 v115, 31, v114
	v_lshlrev_b64 v[116:117], 12, v[114:115]
	v_lshl_add_u64 v[116:117], s[16:17], 0, v[116:117]
	s_or_b64 exec, exec, s[24:25]
	v_lshl_add_u64 v[116:117], v[116:117], 0, v[150:151]
	global_load_dwordx4 v[124:127], v[116:117], off
	global_load_dwordx4 v[176:179], v[116:117], off offset:16
	v_lshlrev_b64 v[120:121], 12, v[114:115]
	v_lshlrev_b64 v[128:129], 11, v[114:115]
	v_lshl_add_u64 v[120:121], s[16:17], 0, v[120:121]
	v_lshl_add_u64 v[128:129], s[64:65], 0, v[128:129]
	v_lshl_add_u64 v[120:121], v[120:121], 0, v[150:151]
	v_lshl_add_u64 v[128:129], v[148:149], 1, v[128:129]
	s_waitcnt vmcnt(1)
	v_pk_add_f32 v[112:113], v[112:113], v[126:127]
	v_pk_add_f32 v[110:111], v[110:111], v[124:125]
	s_waitcnt vmcnt(0)
	v_pk_add_f32 v[108:109], v[108:109], v[178:179]
	v_pk_add_f32 v[106:107], v[106:107], v[176:177]
	global_store_dwordx4 v[120:121], v[110:113], off
	global_store_dwordx4 v[120:121], v[106:109], off offset:16
	v_cvt_pk_bf16_f32 v124, v110, v111
	v_cvt_pk_bf16_f32 v125, v112, v113
	v_cvt_pk_bf16_f32 v126, v106, v107
	v_cvt_pk_bf16_f32 v127, v108, v109
	s_nop 0
	global_load_dwordx4 v[124:127], v[116:117], off offset:512
	s_nop 0
	global_load_dwordx4 v[176:179], v[116:117], off offset:528
	v_mul_f32_e32 v111, v111, v111
	v_mul_f32_e32 v113, v113, v113
	v_mul_f32_e32 v107, v107, v107
	v_mul_f32_e32 v109, v109, v109
	v_fmac_f32_e32 v111, v110, v110
	v_fmac_f32_e32 v113, v112, v112
	v_fmac_f32_e32 v107, v106, v106
	v_fmac_f32_e32 v109, v108, v108
	v_add_f32_e32 v106, v111, v113
	v_add_f32_e32 v107, v107, v109
	v_add_f32_e32 v110, v106, v107
	s_waitcnt vmcnt(1)
	v_pk_add_f32 v[104:105], v[104:105], v[126:127]
	v_pk_add_f32 v[102:103], v[102:103], v[124:125]
	s_waitcnt vmcnt(0)
	v_pk_add_f32 v[108:109], v[100:101], v[178:179]
	v_pk_add_f32 v[106:107], v[98:99], v[176:177]
	v_mul_f32_e32 v98, v103, v103
	v_mul_f32_e32 v99, v105, v105
	v_mul_f32_e32 v100, v107, v107
	v_mul_f32_e32 v101, v109, v109
	v_fmac_f32_e32 v98, v102, v102
	v_fmac_f32_e32 v99, v104, v104
	v_fmac_f32_e32 v100, v106, v106
	v_fmac_f32_e32 v101, v108, v108
	v_add_f32_e32 v98, v98, v99
	v_add_f32_e32 v99, v100, v101
	v_add_f32_e32 v98, v98, v99
	v_add_f32_e32 v98, v110, v98
	ds_bpermute_b32 v99, v122, v98
	global_store_dwordx4 v[120:121], v[102:105], off offset:512
	global_store_dwordx4 v[120:121], v[106:109], off offset:528
	v_cvt_pk_bf16_f32 v100, v102, v103
	v_cvt_pk_bf16_f32 v101, v104, v105
	s_waitcnt lgkmcnt(0)
	v_add_f32_e32 v98, v98, v99
	ds_bpermute_b32 v99, v118, v98
	v_cvt_pk_bf16_f32 v102, v106, v107
	v_cvt_pk_bf16_f32 v103, v108, v109
	s_nop 0
	s_and_saveexec_b64 s[24:25], s[0:1]
	s_cbranch_execz .LBB0_2024
	s_waitcnt lgkmcnt(0)
	v_add_f32_e32 v100, v98, v99
	v_lshl_add_u64 v[98:99], v[114:115], 2, s[10:11]
	global_atomic_add_f32 v[98:99], v100, off
; __device__ __forceinline__ unsigned pk(float lo, float hi) { return pg8::cvt_pk_bf16(lo, hi); }
; __device__ __forceinline__ float dot4(f32x4 v) { return (v[0] * v[0] + v[1] * v[1]) + (v[2] * v[2] + v[3] * v[3]); }
;     __device__ __forceinline__ void operator()(const pg8::f32x4 (&acc)[2][2][4][2], const pg8::Unit& u, int wr, int wc, int fr, int fq) const {
;     ...
;             for (int m = 0; m < 4; ++m) {
;                 const int row = row0 + ai * 128 + m * 16;
;                 const float* xi = (row < MP) ? xin_p + (size_t)row * DM : xin_s + (size_t)(row - MP) * DM;
;                 float sq = 0.f;
; #pragma unroll
;                 for (int bj = 0; bj < 2; ++bj) { const int col = u.pn * 256 + bj * 128 + wc * 32 + 8 * fq;
;                     const f32x4 a0 = *(const f32x4*)(xi + col) + acc[ai][bj][m][0], a1 = *(const f32x4*)(xi + col + 4) + acc[ai][bj][m][1];
;                     *(f32x4*)(xout + (size_t)row * DM + col) = a0; *(f32x4*)(xout + (size_t)row * DM + col + 4) = a1;
;                     u32x4 w; w.x = pk(a0[0], a0[1]); w.y = pk(a0[2], a0[3]); w.z = pk(a1[0], a1[1]); w.w = pk(a1[2], a1[3]);
;                     *(u32x4*)(xb + (size_t)row * DM + col) = w;
;                     sq += dot4(a0) + dot4(a1); }
;                 sq += __shfl_xor(sq, 16); sq += __shfl_xor(sq, 32);
;                 if (fq == 0) atomicAdd(ssout + row, sq);
;             }
.LBB0_2024:
	s_or_b64 exec, exec, s[24:25]
	s_waitcnt lgkmcnt(0)
	v_or_b32_e32 v98, 32, v152
	v_cmp_lt_i32_e32 vcc, s50, v98
	s_and_saveexec_b64 s[24:25], vcc
	s_xor_b64 s[24:25], exec, s[24:25]
	v_add_u32_e32 v138, 0xffffc020, v152
	v_lshlrev_b64 v[100:101], 12, v[138:139]
	v_lshl_add_u64 v[100:101], s[8:9], 0, v[100:101]
	v_mov_b32_e32 v99, v139
	s_andn2_saveexec_b64 s[24:25], s[24:25]
	v_ashrrev_i32_e32 v99, 31, v98
	v_lshlrev_b64 v[100:101], 12, v[98:99]
	v_lshl_add_u64 v[100:101], s[16:17], 0, v[100:101]
	s_or_b64 exec, exec, s[24:25]
	v_lshl_add_u64 v[108:109], v[100:101], 0, v[150:151]
	global_load_dwordx4 v[100:103], v[108:109], off
	global_load_dwordx4 v[104:107], v[108:109], off offset:16
	v_lshlrev_b64 v[110:111], 12, v[98:99]
	v_lshlrev_b64 v[112:113], 11, v[98:99]
	v_lshl_add_u64 v[110:111], s[16:17], 0, v[110:111]
	v_lshl_add_u64 v[112:113], s[64:65], 0, v[112:113]
	v_lshl_add_u64 v[110:111], v[110:111], 0, v[150:151]
	v_lshl_add_u64 v[112:113], v[148:149], 1, v[112:113]
	s_waitcnt vmcnt(1)
	v_pk_add_f32 v[96:97], v[96:97], v[102:103]
	v_pk_add_f32 v[94:95], v[94:95], v[100:101]
	s_waitcnt vmcnt(0)
	v_pk_add_f32 v[92:93], v[92:93], v[106:107]
	v_pk_add_f32 v[90:91], v[90:91], v[104:105]
	global_store_dwordx4 v[110:111], v[94:97], off
	global_store_dwordx4 v[110:111], v[90:93], off offset:16
	v_cvt_pk_bf16_f32 v100, v94, v95
	v_cvt_pk_bf16_f32 v101, v96, v97
	v_cvt_pk_bf16_f32 v102, v90, v91
	v_cvt_pk_bf16_f32 v103, v92, v93
	s_nop 0
	global_load_dwordx4 v[100:103], v[108:109], off offset:512
	s_nop 0
	global_load_dwordx4 v[104:107], v[108:109], off offset:528
	v_mul_f32_e32 v95, v95, v95
	v_mul_f32_e32 v97, v97, v97
	v_mul_f32_e32 v91, v91, v91
	v_mul_f32_e32 v93, v93, v93
	v_fmac_f32_e32 v95, v94, v94
	v_fmac_f32_e32 v97, v96, v96
	v_fmac_f32_e32 v91, v90, v90
	v_fmac_f32_e32 v93, v92, v92
	v_add_f32_e32 v90, v95, v97
	v_add_f32_e32 v91, v91, v93
	v_add_f32_e32 v94, v90, v91
	s_waitcnt vmcnt(1)
	v_pk_add_f32 v[88:89], v[88:89], v[102:103]
	v_pk_add_f32 v[86:87], v[86:87], v[100:101]
	s_waitcnt vmcnt(0)
	v_pk_add_f32 v[92:93], v[84:85], v[106:107]
	v_pk_add_f32 v[90:91], v[82:83], v[104:105]
	v_mul_f32_e32 v82, v87, v87
	v_mul_f32_e32 v83, v89, v89
	v_mul_f32_e32 v84, v91, v91
	v_mul_f32_e32 v85, v93, v93
	v_fmac_f32_e32 v82, v86, v86
	v_fmac_f32_e32 v83, v88, v88
	v_fmac_f32_e32 v84, v90, v90
	v_fmac_f32_e32 v85, v92, v92
	v_add_f32_e32 v82, v82, v83
	v_add_f32_e32 v83, v84, v85
	v_add_f32_e32 v82, v82, v83
	v_add_f32_e32 v82, v94, v82
	ds_bpermute_b32 v83, v122, v82
	global_store_dwordx4 v[110:111], v[86:89], off offset:512
	global_store_dwordx4 v[110:111], v[90:93], off offset:528
	v_cvt_pk_bf16_f32 v84, v86, v87
	v_cvt_pk_bf16_f32 v85, v88, v89
	s_waitcnt lgkmcnt(0)
	v_add_f32_e32 v82, v82, v83
	ds_bpermute_b32 v83, v118, v82
	v_cvt_pk_bf16_f32 v86, v90, v91
	v_cvt_pk_bf16_f32 v87, v92, v93
	s_nop 0
	s_and_saveexec_b64 s[24:25], s[0:1]
	s_cbranch_execz .LBB0_2030
	s_waitcnt lgkmcnt(0)
	v_add_f32_e32 v84, v82, v83
	v_lshl_add_u64 v[82:83], v[98:99], 2, s[10:11]
	global_atomic_add_f32 v[82:83], v84, off
.LBB0_2030:
	s_or_b64 exec, exec, s[24:25]
	s_waitcnt lgkmcnt(0)
	v_or_b32_e32 v82, 48, v152
	v_cmp_lt_i32_e32 vcc, s50, v82
	s_and_saveexec_b64 s[24:25], vcc
	s_xor_b64 s[24:25], exec, s[24:25]
	v_add_u32_e32 v138, 0xffffc030, v152
	v_lshlrev_b64 v[84:85], 12, v[138:139]
	v_lshl_add_u64 v[84:85], s[8:9], 0, v[84:85]
	v_mov_b32_e32 v83, v139
	s_andn2_saveexec_b64 s[24:25], s[24:25]
	v_ashrrev_i32_e32 v83, 31, v82
	v_lshlrev_b64 v[84:85], 12, v[82:83]
	v_lshl_add_u64 v[84:85], s[16:17], 0, v[84:85]
	s_or_b64 exec, exec, s[24:25]
	v_lshl_add_u64 v[92:93], v[84:85], 0, v[150:151]
	global_load_dwordx4 v[84:87], v[92:93], off
	global_load_dwordx4 v[88:91], v[92:93], off offset:16
	v_lshlrev_b64 v[94:95], 12, v[82:83]
	v_lshlrev_b64 v[96:97], 11, v[82:83]
	v_lshl_add_u64 v[94:95], s[16:17], 0, v[94:95]
	v_lshl_add_u64 v[96:97], s[64:65], 0, v[96:97]
	v_lshl_add_u64 v[94:95], v[94:95], 0, v[150:151]
	v_lshl_add_u64 v[96:97], v[148:149], 1, v[96:97]
	s_waitcnt vmcnt(1)
	v_pk_add_f32 v[80:81], v[80:81], v[86:87]
	v_pk_add_f32 v[78:79], v[78:79], v[84:85]
	s_waitcnt vmcnt(0)
	v_pk_add_f32 v[76:77], v[76:77], v[90:91]
	v_pk_add_f32 v[74:75], v[74:75], v[88:89]
	global_store_dwordx4 v[94:95], v[78:81], off
	global_store_dwordx4 v[94:95], v[74:77], off offset:16
	v_cvt_pk_bf16_f32 v84, v78, v79
	v_cvt_pk_bf16_f32 v85, v80, v81
	v_cvt_pk_bf16_f32 v86, v74, v75
	v_cvt_pk_bf16_f32 v87, v76, v77
	s_nop 0
	global_load_dwordx4 v[84:87], v[92:93], off offset:512
	s_nop 0
	global_load_dwordx4 v[88:91], v[92:93], off offset:528
	v_mul_f32_e32 v79, v79, v79
	v_mul_f32_e32 v81, v81, v81
	v_mul_f32_e32 v75, v75, v75
	v_mul_f32_e32 v77, v77, v77
	v_fmac_f32_e32 v79, v78, v78
	v_fmac_f32_e32 v81, v80, v80
	v_fmac_f32_e32 v75, v74, v74
	v_fmac_f32_e32 v77, v76, v76
	v_add_f32_e32 v74, v79, v81
	v_add_f32_e32 v75, v75, v77
	v_add_f32_e32 v78, v74, v75
	s_waitcnt vmcnt(1)
	v_pk_add_f32 v[72:73], v[72:73], v[86:87]
	v_pk_add_f32 v[70:71], v[70:71], v[84:85]
	s_waitcnt vmcnt(0)
	v_pk_add_f32 v[76:77], v[68:69], v[90:91]
	v_pk_add_f32 v[74:75], v[66:67], v[88:89]
	v_mul_f32_e32 v66, v71, v71
	v_mul_f32_e32 v67, v73, v73
	v_mul_f32_e32 v68, v75, v75
	v_mul_f32_e32 v69, v77, v77
	v_fmac_f32_e32 v66, v70, v70
	v_fmac_f32_e32 v67, v72, v72
	v_fmac_f32_e32 v68, v74, v74
	v_fmac_f32_e32 v69, v76, v76
	v_add_f32_e32 v66, v66, v67
	v_add_f32_e32 v67, v68, v69
	v_add_f32_e32 v66, v66, v67
	v_add_f32_e32 v66, v78, v66
	ds_bpermute_b32 v67, v122, v66
	global_store_dwordx4 v[94:95], v[70:73], off offset:512
	global_store_dwordx4 v[94:95], v[74:77], off offset:528
	v_cvt_pk_bf16_f32 v68, v70, v71
	v_cvt_pk_bf16_f32 v69, v72, v73
	s_waitcnt lgkmcnt(0)
	v_add_f32_e32 v66, v66, v67
	ds_bpermute_b32 v67, v118, v66
	v_cvt_pk_bf16_f32 v70, v74, v75
	v_cvt_pk_bf16_f32 v71, v76, v77
	s_nop 0
	s_and_saveexec_b64 s[24:25], s[0:1]
	s_cbranch_execz .LBB0_2036
	s_waitcnt lgkmcnt(0)
	v_add_f32_e32 v68, v66, v67
	v_lshl_add_u64 v[66:67], v[82:83], 2, s[10:11]
	global_atomic_add_f32 v[66:67], v68, off
; __device__ __forceinline__ unsigned pk(float lo, float hi) { return pg8::cvt_pk_bf16(lo, hi); }
; __device__ __forceinline__ float dot4(f32x4 v) { return (v[0] * v[0] + v[1] * v[1]) + (v[2] * v[2] + v[3] * v[3]); }
;     __device__ __forceinline__ void operator()(const pg8::f32x4 (&acc)[2][2][4][2], const pg8::Unit& u, int wr, int wc, int fr, int fq) const {
;     ...
;             for (int m = 0; m < 4; ++m) {
;                 const int row = row0 + ai * 128 + m * 16;
;                 const float* xi = (row < MP) ? xin_p + (size_t)row * DM : xin_s + (size_t)(row - MP) * DM;
;                 float sq = 0.f;
; #pragma unroll
;                 for (int bj = 0; bj < 2; ++bj) { const int col = u.pn * 256 + bj * 128 + wc * 32 + 8 * fq;
;                     const f32x4 a0 = *(const f32x4*)(xi + col) + acc[ai][bj][m][0], a1 = *(const f32x4*)(xi + col + 4) + acc[ai][bj][m][1];
;                     *(f32x4*)(xout + (size_t)row * DM + col) = a0; *(f32x4*)(xout + (size_t)row * DM + col + 4) = a1;
;                     u32x4 w; w.x = pk(a0[0], a0[1]); w.y = pk(a0[2], a0[3]); w.z = pk(a1[0], a1[1]); w.w = pk(a1[2], a1[3]);
;                     *(u32x4*)(xb + (size_t)row * DM + col) = w;
;                     sq += dot4(a0) + dot4(a1); }
;                 sq += __shfl_xor(sq, 16); sq += __shfl_xor(sq, 32);
;                 if (fq == 0) atomicAdd(ssout + row, sq);
;             }
.LBB0_2036:
	s_or_b64 exec, exec, s[24:25]
	s_waitcnt lgkmcnt(0)
	v_add_u32_e32 v66, 0x80, v152
	v_cmp_lt_i32_e32 vcc, s51, v152
	s_and_saveexec_b64 s[24:25], vcc
	s_xor_b64 s[24:25], exec, s[24:25]
	v_add_u32_e32 v138, 0xffffc080, v152
	v_lshlrev_b64 v[68:69], 12, v[138:139]
	v_lshl_add_u64 v[68:69], s[8:9], 0, v[68:69]
	v_mov_b32_e32 v67, v139
	s_andn2_saveexec_b64 s[24:25], s[24:25]
	v_ashrrev_i32_e32 v67, 31, v66
	v_lshlrev_b64 v[68:69], 12, v[66:67]
	v_lshl_add_u64 v[68:69], s[16:17], 0, v[68:69]
	s_or_b64 exec, exec, s[24:25]
	v_lshl_add_u64 v[76:77], v[68:69], 0, v[150:151]
	global_load_dwordx4 v[68:71], v[76:77], off
	global_load_dwordx4 v[72:75], v[76:77], off offset:16
	v_lshlrev_b64 v[78:79], 12, v[66:67]
	v_lshlrev_b64 v[80:81], 11, v[66:67]
	v_lshl_add_u64 v[78:79], s[16:17], 0, v[78:79]
	v_lshl_add_u64 v[80:81], s[64:65], 0, v[80:81]
	v_lshl_add_u64 v[78:79], v[78:79], 0, v[150:151]
	v_lshl_add_u64 v[80:81], v[148:149], 1, v[80:81]
	s_waitcnt vmcnt(1)
	v_pk_add_f32 v[64:65], v[64:65], v[70:71]
	v_pk_add_f32 v[62:63], v[62:63], v[68:69]
	s_waitcnt vmcnt(0)
	v_pk_add_f32 v[60:61], v[60:61], v[74:75]
	v_pk_add_f32 v[58:59], v[58:59], v[72:73]
	global_store_dwordx4 v[78:79], v[62:65], off
	global_store_dwordx4 v[78:79], v[58:61], off offset:16
	v_cvt_pk_bf16_f32 v68, v62, v63
	v_cvt_pk_bf16_f32 v69, v64, v65
	v_cvt_pk_bf16_f32 v70, v58, v59
	v_cvt_pk_bf16_f32 v71, v60, v61
	s_nop 0
	global_load_dwordx4 v[68:71], v[76:77], off offset:512
	s_nop 0
	global_load_dwordx4 v[72:75], v[76:77], off offset:528
	v_mul_f32_e32 v63, v63, v63
	v_mul_f32_e32 v65, v65, v65
	v_mul_f32_e32 v59, v59, v59
	v_mul_f32_e32 v61, v61, v61
	v_fmac_f32_e32 v63, v62, v62
	v_fmac_f32_e32 v65, v64, v64
	v_fmac_f32_e32 v59, v58, v58
	v_fmac_f32_e32 v61, v60, v60
	v_add_f32_e32 v58, v63, v65
	v_add_f32_e32 v59, v59, v61
	v_add_f32_e32 v62, v58, v59
	s_waitcnt vmcnt(1)
	v_pk_add_f32 v[56:57], v[56:57], v[70:71]
	v_pk_add_f32 v[54:55], v[54:55], v[68:69]
	s_waitcnt vmcnt(0)
	v_pk_add_f32 v[60:61], v[52:53], v[74:75]
	v_pk_add_f32 v[58:59], v[50:51], v[72:73]
	v_mul_f32_e32 v50, v55, v55
	v_mul_f32_e32 v51, v57, v57
	v_mul_f32_e32 v52, v59, v59
	v_mul_f32_e32 v53, v61, v61
	v_fmac_f32_e32 v50, v54, v54
	v_fmac_f32_e32 v51, v56, v56
	v_fmac_f32_e32 v52, v58, v58
	v_fmac_f32_e32 v53, v60, v60
	v_add_f32_e32 v50, v50, v51
	v_add_f32_e32 v51, v52, v53
	v_add_f32_e32 v50, v50, v51
	v_add_f32_e32 v50, v62, v50
	ds_bpermute_b32 v51, v122, v50
	global_store_dwordx4 v[78:79], v[54:57], off offset:512
	global_store_dwordx4 v[78:79], v[58:61], off offset:528
	v_cvt_pk_bf16_f32 v52, v54, v55
	v_cvt_pk_bf16_f32 v53, v56, v57
	s_waitcnt lgkmcnt(0)
	v_add_f32_e32 v50, v50, v51
	ds_bpermute_b32 v51, v118, v50
	v_cvt_pk_bf16_f32 v54, v58, v59
	v_cvt_pk_bf16_f32 v55, v60, v61
	s_nop 0
	s_and_saveexec_b64 s[24:25], s[0:1]
	s_cbranch_execz .LBB0_2042
	s_waitcnt lgkmcnt(0)
	v_add_f32_e32 v52, v50, v51
	v_lshl_add_u64 v[50:51], v[66:67], 2, s[10:11]
	global_atomic_add_f32 v[50:51], v52, off
.LBB0_2042:
	s_or_b64 exec, exec, s[24:25]
	s_waitcnt lgkmcnt(0)
	v_add_u32_e32 v50, 0x90, v152
	v_cmp_lt_i32_e32 vcc, s52, v152
	s_and_saveexec_b64 s[24:25], vcc
	s_xor_b64 s[24:25], exec, s[24:25]
	v_add_u32_e32 v138, 0xffffc090, v152
	v_lshlrev_b64 v[52:53], 12, v[138:139]
	v_lshl_add_u64 v[52:53], s[8:9], 0, v[52:53]
	v_mov_b32_e32 v51, v139
	s_andn2_saveexec_b64 s[24:25], s[24:25]
	v_ashrrev_i32_e32 v51, 31, v50
	v_lshlrev_b64 v[52:53], 12, v[50:51]
	v_lshl_add_u64 v[52:53], s[16:17], 0, v[52:53]
	s_or_b64 exec, exec, s[24:25]
	v_lshl_add_u64 v[60:61], v[52:53], 0, v[150:151]
	global_load_dwordx4 v[52:55], v[60:61], off
	global_load_dwordx4 v[56:59], v[60:61], off offset:16
	v_lshlrev_b64 v[62:63], 12, v[50:51]
	v_lshlrev_b64 v[64:65], 11, v[50:51]
	v_lshl_add_u64 v[62:63], s[16:17], 0, v[62:63]
	v_lshl_add_u64 v[64:65], s[64:65], 0, v[64:65]
	v_lshl_add_u64 v[62:63], v[62:63], 0, v[150:151]
	v_lshl_add_u64 v[64:65], v[148:149], 1, v[64:65]
	s_waitcnt vmcnt(1)
	v_pk_add_f32 v[48:49], v[48:49], v[54:55]
	v_pk_add_f32 v[46:47], v[46:47], v[52:53]
	s_waitcnt vmcnt(0)
	v_pk_add_f32 v[44:45], v[44:45], v[58:59]
	v_pk_add_f32 v[42:43], v[42:43], v[56:57]
	global_store_dwordx4 v[62:63], v[46:49], off
	global_store_dwordx4 v[62:63], v[42:45], off offset:16
	v_cvt_pk_bf16_f32 v52, v46, v47
	v_cvt_pk_bf16_f32 v53, v48, v49
	v_cvt_pk_bf16_f32 v54, v42, v43
	v_cvt_pk_bf16_f32 v55, v44, v45
	s_nop 0
	global_load_dwordx4 v[52:55], v[60:61], off offset:512
	s_nop 0
	global_load_dwordx4 v[56:59], v[60:61], off offset:528
	v_mul_f32_e32 v47, v47, v47
	v_mul_f32_e32 v49, v49, v49
	v_mul_f32_e32 v43, v43, v43
	v_mul_f32_e32 v45, v45, v45
	v_fmac_f32_e32 v47, v46, v46
	v_fmac_f32_e32 v49, v48, v48
	v_fmac_f32_e32 v43, v42, v42
	v_fmac_f32_e32 v45, v44, v44
	v_add_f32_e32 v42, v47, v49
	v_add_f32_e32 v43, v43, v45
	v_add_f32_e32 v46, v42, v43
	s_waitcnt vmcnt(1)
	v_pk_add_f32 v[40:41], v[40:41], v[54:55]
	v_pk_add_f32 v[38:39], v[38:39], v[52:53]
	s_waitcnt vmcnt(0)
	v_pk_add_f32 v[44:45], v[36:37], v[58:59]
	v_pk_add_f32 v[42:43], v[34:35], v[56:57]
	v_mul_f32_e32 v34, v39, v39
	v_mul_f32_e32 v35, v41, v41
	v_mul_f32_e32 v36, v43, v43
	v_mul_f32_e32 v37, v45, v45
	v_fmac_f32_e32 v34, v38, v38
	v_fmac_f32_e32 v35, v40, v40
	v_fmac_f32_e32 v36, v42, v42
	v_fmac_f32_e32 v37, v44, v44
	v_add_f32_e32 v34, v34, v35
	v_add_f32_e32 v35, v36, v37
	v_add_f32_e32 v34, v34, v35
	v_add_f32_e32 v34, v46, v34
	ds_bpermute_b32 v35, v122, v34
	global_store_dwordx4 v[62:63], v[38:41], off offset:512
	global_store_dwordx4 v[62:63], v[42:45], off offset:528
	v_cvt_pk_bf16_f32 v36, v38, v39
	v_cvt_pk_bf16_f32 v37, v40, v41
	s_waitcnt lgkmcnt(0)
	v_add_f32_e32 v34, v34, v35
	ds_bpermute_b32 v35, v118, v34
	v_cvt_pk_bf16_f32 v38, v42, v43
	v_cvt_pk_bf16_f32 v39, v44, v45
	s_nop 0
	s_and_saveexec_b64 s[24:25], s[0:1]
	s_cbranch_execz .LBB0_2048
	s_waitcnt lgkmcnt(0)
	v_add_f32_e32 v36, v34, v35
	v_lshl_add_u64 v[34:35], v[50:51], 2, s[10:11]
	global_atomic_add_f32 v[34:35], v36, off
; __device__ __forceinline__ unsigned pk(float lo, float hi) { return pg8::cvt_pk_bf16(lo, hi); }
; __device__ __forceinline__ float dot4(f32x4 v) { return (v[0] * v[0] + v[1] * v[1]) + (v[2] * v[2] + v[3] * v[3]); }
;     __device__ __forceinline__ void operator()(const pg8::f32x4 (&acc)[2][2][4][2], const pg8::Unit& u, int wr, int wc, int fr, int fq) const {
;     ...
;             for (int m = 0; m < 4; ++m) {
;                 const int row = row0 + ai * 128 + m * 16;
;                 const float* xi = (row < MP) ? xin_p + (size_t)row * DM : xin_s + (size_t)(row - MP) * DM;
;                 float sq = 0.f;
; #pragma unroll
;                 for (int bj = 0; bj < 2; ++bj) { const int col = u.pn * 256 + bj * 128 + wc * 32 + 8 * fq;
;                     const f32x4 a0 = *(const f32x4*)(xi + col) + acc[ai][bj][m][0], a1 = *(const f32x4*)(xi + col + 4) + acc[ai][bj][m][1];
;                     *(f32x4*)(xout + (size_t)row * DM + col) = a0; *(f32x4*)(xout + (size_t)row * DM + col + 4) = a1;
;                     u32x4 w; w.x = pk(a0[0], a0[1]); w.y = pk(a0[2], a0[3]); w.z = pk(a1[0], a1[1]); w.w = pk(a1[2], a1[3]);
;                     *(u32x4*)(xb + (size_t)row * DM + col) = w;
;                     sq += dot4(a0) + dot4(a1); }
;                 sq += __shfl_xor(sq, 16); sq += __shfl_xor(sq, 32);
;                 if (fq == 0) atomicAdd(ssout + row, sq);
;             }
.LBB0_2048:
	s_or_b64 exec, exec, s[24:25]
	s_waitcnt lgkmcnt(0)
	v_add_u32_e32 v34, 0xa0, v152
	v_cmp_lt_i32_e32 vcc, s53, v152
	s_and_saveexec_b64 s[24:25], vcc
	s_xor_b64 s[24:25], exec, s[24:25]
	v_add_u32_e32 v138, 0xffffc0a0, v152
	v_lshlrev_b64 v[36:37], 12, v[138:139]
	v_lshl_add_u64 v[36:37], s[8:9], 0, v[36:37]
	v_mov_b32_e32 v35, v139
	s_andn2_saveexec_b64 s[24:25], s[24:25]
	v_ashrrev_i32_e32 v35, 31, v34
	v_lshlrev_b64 v[36:37], 12, v[34:35]
	v_lshl_add_u64 v[36:37], s[16:17], 0, v[36:37]
	s_or_b64 exec, exec, s[24:25]
	v_lshl_add_u64 v[44:45], v[36:37], 0, v[150:151]
	global_load_dwordx4 v[36:39], v[44:45], off
	global_load_dwordx4 v[40:43], v[44:45], off offset:16
	v_lshlrev_b64 v[46:47], 12, v[34:35]
	v_lshlrev_b64 v[48:49], 11, v[34:35]
	v_lshl_add_u64 v[46:47], s[16:17], 0, v[46:47]
	v_lshl_add_u64 v[48:49], s[64:65], 0, v[48:49]
	v_lshl_add_u64 v[46:47], v[46:47], 0, v[150:151]
	v_lshl_add_u64 v[48:49], v[148:149], 1, v[48:49]
	s_waitcnt vmcnt(1)
	v_pk_add_f32 v[32:33], v[32:33], v[38:39]
	v_pk_add_f32 v[30:31], v[30:31], v[36:37]
	s_waitcnt vmcnt(0)
	v_pk_add_f32 v[28:29], v[28:29], v[42:43]
	v_pk_add_f32 v[26:27], v[26:27], v[40:41]
	global_store_dwordx4 v[46:47], v[30:33], off
	global_store_dwordx4 v[46:47], v[26:29], off offset:16
	v_cvt_pk_bf16_f32 v36, v30, v31
	v_cvt_pk_bf16_f32 v37, v32, v33
	v_cvt_pk_bf16_f32 v38, v26, v27
	v_cvt_pk_bf16_f32 v39, v28, v29
	s_nop 0
	global_load_dwordx4 v[36:39], v[44:45], off offset:512
	s_nop 0
	global_load_dwordx4 v[40:43], v[44:45], off offset:528
	v_mul_f32_e32 v31, v31, v31
	v_mul_f32_e32 v33, v33, v33
	v_mul_f32_e32 v27, v27, v27
	v_mul_f32_e32 v29, v29, v29
	v_fmac_f32_e32 v31, v30, v30
	v_fmac_f32_e32 v33, v32, v32
	v_fmac_f32_e32 v27, v26, v26
	v_fmac_f32_e32 v29, v28, v28
	v_add_f32_e32 v26, v31, v33
	v_add_f32_e32 v27, v27, v29
	v_add_f32_e32 v30, v26, v27
	s_waitcnt vmcnt(1)
	v_pk_add_f32 v[24:25], v[24:25], v[38:39]
	v_pk_add_f32 v[22:23], v[22:23], v[36:37]
	s_waitcnt vmcnt(0)
	v_pk_add_f32 v[28:29], v[20:21], v[42:43]
	v_pk_add_f32 v[26:27], v[18:19], v[40:41]
	v_mul_f32_e32 v18, v23, v23
	v_mul_f32_e32 v19, v25, v25
	v_mul_f32_e32 v20, v27, v27
	v_mul_f32_e32 v21, v29, v29
	v_fmac_f32_e32 v18, v22, v22
	v_fmac_f32_e32 v19, v24, v24
	v_fmac_f32_e32 v20, v26, v26
	v_fmac_f32_e32 v21, v28, v28
	v_add_f32_e32 v18, v18, v19
	v_add_f32_e32 v19, v20, v21
	v_add_f32_e32 v18, v18, v19
	v_add_f32_e32 v18, v30, v18
	ds_bpermute_b32 v19, v122, v18
	global_store_dwordx4 v[46:47], v[22:25], off offset:512
	global_store_dwordx4 v[46:47], v[26:29], off offset:528
	v_cvt_pk_bf16_f32 v20, v22, v23
	v_cvt_pk_bf16_f32 v21, v24, v25
	s_waitcnt lgkmcnt(0)
	v_add_f32_e32 v18, v18, v19
	ds_bpermute_b32 v19, v118, v18
	v_cvt_pk_bf16_f32 v22, v26, v27
	v_cvt_pk_bf16_f32 v23, v28, v29
	s_nop 0
	s_and_saveexec_b64 s[24:25], s[0:1]
	s_cbranch_execz .LBB0_2054
	s_waitcnt lgkmcnt(0)
	v_add_f32_e32 v20, v18, v19
	v_lshl_add_u64 v[18:19], v[34:35], 2, s[10:11]
	global_atomic_add_f32 v[18:19], v20, off
.LBB0_2054:
	s_or_b64 exec, exec, s[24:25]
	s_waitcnt lgkmcnt(0)
	v_add_u32_e32 v18, 0xb0, v152
	v_cmp_lt_i32_e32 vcc, s54, v152
	s_and_saveexec_b64 s[24:25], vcc
	s_xor_b64 s[24:25], exec, s[24:25]
	v_add_u32_e32 v138, 0xffffc0b0, v152
	v_lshlrev_b64 v[20:21], 12, v[138:139]
	v_lshl_add_u64 v[20:21], s[8:9], 0, v[20:21]
	v_mov_b32_e32 v19, v139
	s_andn2_saveexec_b64 s[24:25], s[24:25]
	v_ashrrev_i32_e32 v19, 31, v18
	v_lshlrev_b64 v[20:21], 12, v[18:19]
	v_lshl_add_u64 v[20:21], s[16:17], 0, v[20:21]
	s_or_b64 exec, exec, s[24:25]
	v_lshl_add_u64 v[28:29], v[20:21], 0, v[150:151]
	global_load_dwordx4 v[20:23], v[28:29], off
	global_load_dwordx4 v[24:27], v[28:29], off offset:16
	v_lshlrev_b64 v[30:31], 12, v[18:19]
	v_lshlrev_b64 v[32:33], 11, v[18:19]
	v_lshl_add_u64 v[30:31], s[16:17], 0, v[30:31]
	v_lshl_add_u64 v[32:33], s[64:65], 0, v[32:33]
	v_lshl_add_u64 v[30:31], v[30:31], 0, v[150:151]
	v_lshl_add_u64 v[32:33], v[148:149], 1, v[32:33]
	s_waitcnt vmcnt(1)
	v_pk_add_f32 v[16:17], v[16:17], v[22:23]
	v_pk_add_f32 v[14:15], v[14:15], v[20:21]
	s_waitcnt vmcnt(0)
	v_pk_add_f32 v[12:13], v[12:13], v[26:27]
	v_pk_add_f32 v[10:11], v[10:11], v[24:25]
	global_store_dwordx4 v[30:31], v[14:17], off
	global_store_dwordx4 v[30:31], v[10:13], off offset:16
	v_cvt_pk_bf16_f32 v20, v14, v15
	v_cvt_pk_bf16_f32 v21, v16, v17
	v_cvt_pk_bf16_f32 v22, v10, v11
	v_cvt_pk_bf16_f32 v23, v12, v13
	s_nop 0
	global_load_dwordx4 v[20:23], v[28:29], off offset:512
	s_nop 0
	global_load_dwordx4 v[24:27], v[28:29], off offset:528
	v_mul_f32_e32 v15, v15, v15
	v_mul_f32_e32 v17, v17, v17
	v_mul_f32_e32 v11, v11, v11
	v_mul_f32_e32 v13, v13, v13
	v_fmac_f32_e32 v15, v14, v14
	v_fmac_f32_e32 v17, v16, v16
	v_fmac_f32_e32 v11, v10, v10
	v_fmac_f32_e32 v13, v12, v12
	v_add_f32_e32 v10, v15, v17
	v_add_f32_e32 v11, v11, v13
	v_add_f32_e32 v14, v10, v11
	s_waitcnt vmcnt(1)
	v_pk_add_f32 v[8:9], v[8:9], v[22:23]
	v_pk_add_f32 v[6:7], v[6:7], v[20:21]
	s_waitcnt vmcnt(0)
	v_pk_add_f32 v[12:13], v[4:5], v[26:27]
	v_pk_add_f32 v[10:11], v[2:3], v[24:25]
	v_mul_f32_e32 v2, v7, v7
	v_mul_f32_e32 v3, v9, v9
	v_mul_f32_e32 v4, v11, v11
	v_mul_f32_e32 v5, v13, v13
	v_fmac_f32_e32 v2, v6, v6
	v_fmac_f32_e32 v3, v8, v8
	v_fmac_f32_e32 v4, v10, v10
	v_fmac_f32_e32 v5, v12, v12
	v_add_f32_e32 v2, v2, v3
	v_add_f32_e32 v3, v4, v5
	v_add_f32_e32 v2, v2, v3
	v_add_f32_e32 v2, v14, v2
	ds_bpermute_b32 v3, v122, v2
	global_store_dwordx4 v[30:31], v[6:9], off offset:512
	global_store_dwordx4 v[30:31], v[10:13], off offset:528
	v_cvt_pk_bf16_f32 v4, v6, v7
	v_cvt_pk_bf16_f32 v5, v8, v9
	s_waitcnt lgkmcnt(0)
	v_add_f32_e32 v2, v2, v3
	ds_bpermute_b32 v3, v118, v2
	v_cvt_pk_bf16_f32 v6, v10, v11
	v_cvt_pk_bf16_f32 v7, v12, v13
	s_nop 0
	s_and_saveexec_b64 s[24:25], s[0:1]
	s_cbranch_execz .LBB0_2060
	s_waitcnt lgkmcnt(0)
	v_add_f32_e32 v4, v2, v3
	v_lshl_add_u64 v[2:3], v[18:19], 2, s[10:11]
	global_atomic_add_f32 v[2:3], v4, off
